# ssd_out grouped-RMSNorm pass re-mapped to 8 contiguous channels per lane: dwordx4 loads/stores (half the vector-memory instructions), row sums by one LDS read + 8-lane DPP reduction
# speedup vs baseline: 1.0238x; 1.0238x over previous
; __device__ __forceinline__ unsigned cvt_pk_bf16(float lo, float hi) { unsigned r; asm volatile("v_cvt_pk_bf16_f32 %0, %1, %2" : "=v"(r) : "v"(lo), "v"(hi)); return r; }
; __device__ __forceinline__ float bflo(unsigned w) { return __uint_as_float(w << 16); }
; __device__ __forceinline__ float bfhi(unsigned w) { return __uint_as_float(w & 0xffff0000u); }
; __device__ void phase_ssd_out(KP P, int layer, LAS unsigned char* lds) {
;     ...
;         {
;             const float* nw = P->ssd_norm + layer * 1024 + h * 64; f32x4 nwv[4];
; #pragma unroll
;             for (int pt = 0; pt < 4; ++pt) nwv[pt] = *(const f32x4*)(nw + pt * 16 + q * 4);
; #pragma unroll
;             for (int lt = 0; lt < 8; ++lt) { const int l = lt * 16 + r; float t = 0.f;
; #pragma unroll
;                 for (int w = 0; w < 8; ++w) t += red[w * 128 + l];
;                 const float rstd = rsqrtf(t * (1.f / 512.f) + EPS);
;                 bf16_t* zp = zbase + (long)l * PW + q * 4; u32x2 v[4];
; #pragma unroll
;                 for (int pt = 0; pt < 4; ++pt) v[pt] = *(const u32x2*)(zp + pt * 16);
; #pragma unroll
;                 for (int pt = 0; pt < 4; ++pt) { u32x2 o; o.x = cvt_pk_bf16(bflo(v[pt].x) * rstd * nwv[pt][0], bfhi(v[pt].x) * rstd * nwv[pt][1]);
;                     o.y = cvt_pk_bf16(bflo(v[pt].y) * rstd * nwv[pt][2], bfhi(v[pt].y) * rstd * nwv[pt][3]); *(u32x2*)(zp + pt * 16) = o; }
;                 }
.LBB0_23:
	s_waitcnt vmcnt(0) lgkmcnt(0)
	s_barrier
	s_load_dwordx2 s[10:11], s[36:37], 0x50
	v_lshrrev_b32_e32 v138, 5, v197
	v_lshrrev_b32_e32 v139, 1, v156
	v_add_u32_e32 v138, v138, v139
	v_bfe_u32 v139, v197, 2, 3
	v_mul_u32_u24_e32 v16, 0x2200, v138
	v_lshl_add_u32 v16, v139, 4, v16
	v_mov_b32_e32 v17, 0
	v_lshl_add_u64 v[16:17], v[182:183], 0, v[16:17]
	v_lshlrev_b32_e32 v140, 9, v139
	v_lshl_add_u32 v140, v138, 2, v140
	v_add_u32_e32 v140, 0xb000, v140
	ds_read2_b32 v[112:113], v140 offset0:0 offset1:8
	ds_read2_b32 v[114:115], v140 offset0:16 offset1:24
	ds_read2_b32 v[116:117], v140 offset0:32 offset1:40
	ds_read2_b32 v[118:119], v140 offset0:48 offset1:56
	ds_read2_b32 v[120:121], v140 offset0:64 offset1:72
	ds_read2_b32 v[122:123], v140 offset0:80 offset1:88
	ds_read2_b32 v[124:125], v140 offset0:96 offset1:104
	ds_read2_b32 v[126:127], v140 offset0:112 offset1:120
	v_add_co_u32_e32 v18, vcc, 0x11000, v16
	s_nop 1
	v_addc_co_u32_e32 v19, vcc, 0, v17, vcc
	v_add_co_u32_e32 v20, vcc, 0x11000, v18
	s_nop 1
	v_addc_co_u32_e32 v21, vcc, 0, v19, vcc
	v_add_co_u32_e32 v22, vcc, 0x11000, v20
	s_nop 1
	v_addc_co_u32_e32 v23, vcc, 0, v21, vcc
	v_add_co_u32_e32 v24, vcc, 0x11000, v22
	s_nop 1
	v_addc_co_u32_e32 v25, vcc, 0, v23, vcc
	v_add_co_u32_e32 v26, vcc, 0x11000, v24
	s_nop 1
	v_addc_co_u32_e32 v27, vcc, 0, v25, vcc
	v_add_co_u32_e32 v28, vcc, 0x11000, v26
	s_nop 1
	v_addc_co_u32_e32 v29, vcc, 0, v27, vcc
	v_add_co_u32_e32 v30, vcc, 0x11000, v28
	s_nop 1
	v_addc_co_u32_e32 v31, vcc, 0, v29, vcc
	v_add_co_u32_e32 v32, vcc, 0x11000, v30
	s_nop 1
	v_addc_co_u32_e32 v33, vcc, 0, v31, vcc
	v_add_co_u32_e32 v34, vcc, 0x11000, v32
	s_nop 1
	v_addc_co_u32_e32 v35, vcc, 0, v33, vcc
	v_add_co_u32_e32 v36, vcc, 0x11000, v34
	s_nop 1
	v_addc_co_u32_e32 v37, vcc, 0, v35, vcc
	v_add_co_u32_e32 v38, vcc, 0x11000, v36
	s_nop 1
	v_addc_co_u32_e32 v39, vcc, 0, v37, vcc
	v_add_co_u32_e32 v40, vcc, 0x11000, v38
	s_nop 1
	v_addc_co_u32_e32 v41, vcc, 0, v39, vcc
	v_add_co_u32_e32 v42, vcc, 0x11000, v40
	s_nop 1
	v_addc_co_u32_e32 v43, vcc, 0, v41, vcc
	v_add_co_u32_e32 v44, vcc, 0x11000, v42
	s_nop 1
	v_addc_co_u32_e32 v45, vcc, 0, v43, vcc
	v_add_co_u32_e32 v46, vcc, 0x11000, v44
	s_nop 1
	v_addc_co_u32_e32 v47, vcc, 0, v45, vcc
	global_load_dwordx4 v[48:51], v[16:17], off offset:2560
	global_load_dwordx4 v[52:55], v[18:19], off offset:2560
	global_load_dwordx4 v[56:59], v[20:21], off offset:2560
	global_load_dwordx4 v[60:63], v[22:23], off offset:2560
	v_lshlrev_b32_e32 v128, 5, v139
	v_mov_b32_e32 v129, 0
	s_waitcnt lgkmcnt(0)
	s_add_u32 s10, s10, s8
	s_addc_u32 s11, s11, s9
	v_lshl_add_u64 v[142:143], v[180:181], 2, s[10:11]
	v_lshl_add_u64 v[142:143], v[142:143], 0, v[128:129]
	global_load_dwordx4 v[0:3], v[142:143], off
	global_load_dwordx4 v[4:7], v[142:143], off offset:16
	global_load_dwordx4 v[64:67], v[24:25], off offset:2560
	global_load_dwordx4 v[68:71], v[26:27], off offset:2560
	global_load_dwordx4 v[72:75], v[28:29], off offset:2560
	global_load_dwordx4 v[76:79], v[30:31], off offset:2560
	global_load_dwordx4 v[80:83], v[32:33], off offset:2560
	global_load_dwordx4 v[84:87], v[34:35], off offset:2560
	global_load_dwordx4 v[88:91], v[36:37], off offset:2560
	global_load_dwordx4 v[92:95], v[38:39], off offset:2560
	global_load_dwordx4 v[96:99], v[40:41], off offset:2560
	global_load_dwordx4 v[100:103], v[42:43], off offset:2560
	global_load_dwordx4 v[104:107], v[44:45], off offset:2560
	global_load_dwordx4 v[108:111], v[46:47], off offset:2560
	v_add_f32_dpp v112, v112, v112 quad_perm:[1,0,3,2] row_mask:0xf bank_mask:0xf
	v_add_f32_dpp v113, v113, v113 quad_perm:[1,0,3,2] row_mask:0xf bank_mask:0xf
	v_add_f32_dpp v114, v114, v114 quad_perm:[1,0,3,2] row_mask:0xf bank_mask:0xf
	v_add_f32_dpp v115, v115, v115 quad_perm:[1,0,3,2] row_mask:0xf bank_mask:0xf
	v_add_f32_dpp v116, v116, v116 quad_perm:[1,0,3,2] row_mask:0xf bank_mask:0xf
	v_add_f32_dpp v117, v117, v117 quad_perm:[1,0,3,2] row_mask:0xf bank_mask:0xf
	v_add_f32_dpp v118, v118, v118 quad_perm:[1,0,3,2] row_mask:0xf bank_mask:0xf
	v_add_f32_dpp v119, v119, v119 quad_perm:[1,0,3,2] row_mask:0xf bank_mask:0xf
	v_add_f32_dpp v120, v120, v120 quad_perm:[1,0,3,2] row_mask:0xf bank_mask:0xf
	v_add_f32_dpp v121, v121, v121 quad_perm:[1,0,3,2] row_mask:0xf bank_mask:0xf
	v_add_f32_dpp v122, v122, v122 quad_perm:[1,0,3,2] row_mask:0xf bank_mask:0xf
	v_add_f32_dpp v123, v123, v123 quad_perm:[1,0,3,2] row_mask:0xf bank_mask:0xf
	v_add_f32_dpp v124, v124, v124 quad_perm:[1,0,3,2] row_mask:0xf bank_mask:0xf
	v_add_f32_dpp v125, v125, v125 quad_perm:[1,0,3,2] row_mask:0xf bank_mask:0xf
	v_add_f32_dpp v126, v126, v126 quad_perm:[1,0,3,2] row_mask:0xf bank_mask:0xf
	v_add_f32_dpp v127, v127, v127 quad_perm:[1,0,3,2] row_mask:0xf bank_mask:0xf
	v_add_f32_dpp v112, v112, v112 quad_perm:[2,3,0,1] row_mask:0xf bank_mask:0xf
	v_add_f32_dpp v113, v113, v113 quad_perm:[2,3,0,1] row_mask:0xf bank_mask:0xf
	v_add_f32_dpp v114, v114, v114 quad_perm:[2,3,0,1] row_mask:0xf bank_mask:0xf
	v_add_f32_dpp v115, v115, v115 quad_perm:[2,3,0,1] row_mask:0xf bank_mask:0xf
	v_add_f32_dpp v116, v116, v116 quad_perm:[2,3,0,1] row_mask:0xf bank_mask:0xf
	v_add_f32_dpp v117, v117, v117 quad_perm:[2,3,0,1] row_mask:0xf bank_mask:0xf
	v_add_f32_dpp v118, v118, v118 quad_perm:[2,3,0,1] row_mask:0xf bank_mask:0xf
	v_add_f32_dpp v119, v119, v119 quad_perm:[2,3,0,1] row_mask:0xf bank_mask:0xf
	v_add_f32_dpp v120, v120, v120 quad_perm:[2,3,0,1] row_mask:0xf bank_mask:0xf
	v_add_f32_dpp v121, v121, v121 quad_perm:[2,3,0,1] row_mask:0xf bank_mask:0xf
	v_add_f32_dpp v122, v122, v122 quad_perm:[2,3,0,1] row_mask:0xf bank_mask:0xf
; __device__ __forceinline__ unsigned cvt_pk_bf16(float lo, float hi) { unsigned r; asm volatile("v_cvt_pk_bf16_f32 %0, %1, %2" : "=v"(r) : "v"(lo), "v"(hi)); return r; }
; __device__ __forceinline__ float bflo(unsigned w) { return __uint_as_float(w << 16); }
; __device__ __forceinline__ float bfhi(unsigned w) { return __uint_as_float(w & 0xffff0000u); }
; __device__ void phase_ssd_out(KP P, int layer, LAS unsigned char* lds) {
;     ...
;             for (int lt = 0; lt < 8; ++lt) { const int l = lt * 16 + r; float t = 0.f;
; #pragma unroll
;                 for (int w = 0; w < 8; ++w) t += red[w * 128 + l];
;                 const float rstd = rsqrtf(t * (1.f / 512.f) + EPS);
;                 bf16_t* zp = zbase + (long)l * PW + q * 4; u32x2 v[4];
; #pragma unroll
;                 for (int pt = 0; pt < 4; ++pt) v[pt] = *(const u32x2*)(zp + pt * 16);
; #pragma unroll
;                 for (int pt = 0; pt < 4; ++pt) { u32x2 o; o.x = cvt_pk_bf16(bflo(v[pt].x) * rstd * nwv[pt][0], bfhi(v[pt].x) * rstd * nwv[pt][1]);
;                     o.y = cvt_pk_bf16(bflo(v[pt].y) * rstd * nwv[pt][2], bfhi(v[pt].y) * rstd * nwv[pt][3]); *(u32x2*)(zp + pt * 16) = o; }
;                 }
	v_add_f32_dpp v123, v123, v123 quad_perm:[2,3,0,1] row_mask:0xf bank_mask:0xf
	v_add_f32_dpp v124, v124, v124 quad_perm:[2,3,0,1] row_mask:0xf bank_mask:0xf
	v_add_f32_dpp v125, v125, v125 quad_perm:[2,3,0,1] row_mask:0xf bank_mask:0xf
	v_add_f32_dpp v126, v126, v126 quad_perm:[2,3,0,1] row_mask:0xf bank_mask:0xf
	v_add_f32_dpp v127, v127, v127 quad_perm:[2,3,0,1] row_mask:0xf bank_mask:0xf
	v_add_f32_dpp v112, v112, v112 row_half_mirror row_mask:0xf bank_mask:0xf
	v_add_f32_dpp v113, v113, v113 row_half_mirror row_mask:0xf bank_mask:0xf
	v_add_f32_dpp v114, v114, v114 row_half_mirror row_mask:0xf bank_mask:0xf
	v_add_f32_dpp v115, v115, v115 row_half_mirror row_mask:0xf bank_mask:0xf
	v_add_f32_dpp v116, v116, v116 row_half_mirror row_mask:0xf bank_mask:0xf
	v_add_f32_dpp v117, v117, v117 row_half_mirror row_mask:0xf bank_mask:0xf
	v_add_f32_dpp v118, v118, v118 row_half_mirror row_mask:0xf bank_mask:0xf
	v_add_f32_dpp v119, v119, v119 row_half_mirror row_mask:0xf bank_mask:0xf
	v_add_f32_dpp v120, v120, v120 row_half_mirror row_mask:0xf bank_mask:0xf
	v_add_f32_dpp v121, v121, v121 row_half_mirror row_mask:0xf bank_mask:0xf
	v_add_f32_dpp v122, v122, v122 row_half_mirror row_mask:0xf bank_mask:0xf
	v_add_f32_dpp v123, v123, v123 row_half_mirror row_mask:0xf bank_mask:0xf
	v_add_f32_dpp v124, v124, v124 row_half_mirror row_mask:0xf bank_mask:0xf
	v_add_f32_dpp v125, v125, v125 row_half_mirror row_mask:0xf bank_mask:0xf
	v_add_f32_dpp v126, v126, v126 row_half_mirror row_mask:0xf bank_mask:0xf
	v_add_f32_dpp v127, v127, v127 row_half_mirror row_mask:0xf bank_mask:0xf
	v_fmamk_f32 v112, v112, 0x3b000000, v209
	v_fmamk_f32 v113, v113, 0x3b000000, v209
	v_fmamk_f32 v114, v114, 0x3b000000, v209
	v_fmamk_f32 v115, v115, 0x3b000000, v209
	v_fmamk_f32 v116, v116, 0x3b000000, v209
	v_fmamk_f32 v117, v117, 0x3b000000, v209
	v_fmamk_f32 v118, v118, 0x3b000000, v209
	v_fmamk_f32 v119, v119, 0x3b000000, v209
	v_fmamk_f32 v120, v120, 0x3b000000, v209
	v_fmamk_f32 v121, v121, 0x3b000000, v209
	v_fmamk_f32 v122, v122, 0x3b000000, v209
	v_fmamk_f32 v123, v123, 0x3b000000, v209
	v_fmamk_f32 v124, v124, 0x3b000000, v209
	v_fmamk_f32 v125, v125, 0x3b000000, v209
	v_fmamk_f32 v126, v126, 0x3b000000, v209
	v_fmamk_f32 v127, v127, 0x3b000000, v209
	v_rsq_f32_e32 v112, v112
	v_rsq_f32_e32 v113, v113
	v_rsq_f32_e32 v114, v114
	v_rsq_f32_e32 v115, v115
	v_rsq_f32_e32 v116, v116
	v_rsq_f32_e32 v117, v117
	v_rsq_f32_e32 v118, v118
	v_rsq_f32_e32 v119, v119
	v_rsq_f32_e32 v120, v120
	v_rsq_f32_e32 v121, v121
	v_rsq_f32_e32 v122, v122
	v_rsq_f32_e32 v123, v123
	v_rsq_f32_e32 v124, v124
	v_rsq_f32_e32 v125, v125
	v_rsq_f32_e32 v126, v126
	v_rsq_f32_e32 v127, v127
	s_mov_b32 s10, 0xffff0000
	s_waitcnt vmcnt(12)
	v_lshlrev_b32_e32 v8, 16, v48
	v_and_b32_e32 v9, s10, v48
	v_lshlrev_b32_e32 v10, 16, v49
	v_and_b32_e32 v11, s10, v49
	v_lshlrev_b32_e32 v12, 16, v50
	v_and_b32_e32 v13, s10, v50
	v_lshlrev_b32_e32 v14, 16, v51
	v_and_b32_e32 v15, s10, v51
	v_pk_mul_f32 v[8:9], v[8:9], v[112:113] op_sel_hi:[1,0]
	v_pk_mul_f32 v[10:11], v[10:11], v[112:113] op_sel_hi:[1,0]
	v_pk_mul_f32 v[12:13], v[12:13], v[112:113] op_sel_hi:[1,0]
	v_pk_mul_f32 v[14:15], v[14:15], v[112:113] op_sel_hi:[1,0]
	v_pk_mul_f32 v[8:9], v[8:9], v[0:1]
	v_pk_mul_f32 v[10:11], v[10:11], v[2:3]
	v_pk_mul_f32 v[12:13], v[12:13], v[4:5]
	v_pk_mul_f32 v[14:15], v[14:15], v[6:7]
	v_cvt_pk_bf16_f32 v48, v8, v9
	v_cvt_pk_bf16_f32 v49, v10, v11
	v_cvt_pk_bf16_f32 v50, v12, v13
	v_cvt_pk_bf16_f32 v51, v14, v15
	global_store_dwordx4 v[16:17], v[48:51], off offset:2560
	s_waitcnt vmcnt(15)
	v_lshlrev_b32_e32 v8, 16, v52
	v_and_b32_e32 v9, s10, v52
	v_lshlrev_b32_e32 v10, 16, v53
	v_and_b32_e32 v11, s10, v53
	v_lshlrev_b32_e32 v12, 16, v54
	v_and_b32_e32 v13, s10, v54
	v_lshlrev_b32_e32 v14, 16, v55
	v_and_b32_e32 v15, s10, v55
	v_pk_mul_f32 v[8:9], v[8:9], v[112:113] op_sel:[0,1] op_sel_hi:[1,1]
	v_pk_mul_f32 v[10:11], v[10:11], v[112:113] op_sel:[0,1] op_sel_hi:[1,1]
	v_pk_mul_f32 v[12:13], v[12:13], v[112:113] op_sel:[0,1] op_sel_hi:[1,1]
	v_pk_mul_f32 v[14:15], v[14:15], v[112:113] op_sel:[0,1] op_sel_hi:[1,1]
	v_pk_mul_f32 v[8:9], v[8:9], v[0:1]
	v_pk_mul_f32 v[10:11], v[10:11], v[2:3]
	v_pk_mul_f32 v[12:13], v[12:13], v[4:5]
	v_pk_mul_f32 v[14:15], v[14:15], v[6:7]
	v_cvt_pk_bf16_f32 v52, v8, v9
	v_cvt_pk_bf16_f32 v53, v10, v11
	v_cvt_pk_bf16_f32 v54, v12, v13
	v_cvt_pk_bf16_f32 v55, v14, v15
	global_store_dwordx4 v[18:19], v[52:55], off offset:2560
	s_waitcnt vmcnt(15)
	v_lshlrev_b32_e32 v8, 16, v56
	v_and_b32_e32 v9, s10, v56
	v_lshlrev_b32_e32 v10, 16, v57
	v_and_b32_e32 v11, s10, v57
	v_lshlrev_b32_e32 v12, 16, v58
	v_and_b32_e32 v13, s10, v58
	v_lshlrev_b32_e32 v14, 16, v59
	v_and_b32_e32 v15, s10, v59
	v_pk_mul_f32 v[8:9], v[8:9], v[114:115] op_sel_hi:[1,0]
	v_pk_mul_f32 v[10:11], v[10:11], v[114:115] op_sel_hi:[1,0]
	v_pk_mul_f32 v[12:13], v[12:13], v[114:115] op_sel_hi:[1,0]
	v_pk_mul_f32 v[14:15], v[14:15], v[114:115] op_sel_hi:[1,0]
	v_pk_mul_f32 v[8:9], v[8:9], v[0:1]
	v_pk_mul_f32 v[10:11], v[10:11], v[2:3]
	v_pk_mul_f32 v[12:13], v[12:13], v[4:5]
	v_pk_mul_f32 v[14:15], v[14:15], v[6:7]
	v_cvt_pk_bf16_f32 v56, v8, v9
	v_cvt_pk_bf16_f32 v57, v10, v11
	v_cvt_pk_bf16_f32 v58, v12, v13
	v_cvt_pk_bf16_f32 v59, v14, v15
	global_store_dwordx4 v[20:21], v[56:59], off offset:2560
	s_waitcnt vmcnt(15)
; __device__ __forceinline__ unsigned cvt_pk_bf16(float lo, float hi) { unsigned r; asm volatile("v_cvt_pk_bf16_f32 %0, %1, %2" : "=v"(r) : "v"(lo), "v"(hi)); return r; }
; __device__ __forceinline__ float bflo(unsigned w) { return __uint_as_float(w << 16); }
; __device__ __forceinline__ float bfhi(unsigned w) { return __uint_as_float(w & 0xffff0000u); }
; __device__ void phase_ssd_out(KP P, int layer, LAS unsigned char* lds) {
;     ...
;             for (int lt = 0; lt < 8; ++lt) { const int l = lt * 16 + r; float t = 0.f;
; #pragma unroll
;                 for (int w = 0; w < 8; ++w) t += red[w * 128 + l];
;                 const float rstd = rsqrtf(t * (1.f / 512.f) + EPS);
;                 bf16_t* zp = zbase + (long)l * PW + q * 4; u32x2 v[4];
; #pragma unroll
;                 for (int pt = 0; pt < 4; ++pt) v[pt] = *(const u32x2*)(zp + pt * 16);
; #pragma unroll
;                 for (int pt = 0; pt < 4; ++pt) { u32x2 o; o.x = cvt_pk_bf16(bflo(v[pt].x) * rstd * nwv[pt][0], bfhi(v[pt].x) * rstd * nwv[pt][1]);
;                     o.y = cvt_pk_bf16(bflo(v[pt].y) * rstd * nwv[pt][2], bfhi(v[pt].y) * rstd * nwv[pt][3]); *(u32x2*)(zp + pt * 16) = o; }
;                 }
	v_lshlrev_b32_e32 v8, 16, v60
	v_and_b32_e32 v9, s10, v60
	v_lshlrev_b32_e32 v10, 16, v61
	v_and_b32_e32 v11, s10, v61
	v_lshlrev_b32_e32 v12, 16, v62
	v_and_b32_e32 v13, s10, v62
	v_lshlrev_b32_e32 v14, 16, v63
	v_and_b32_e32 v15, s10, v63
	v_pk_mul_f32 v[8:9], v[8:9], v[114:115] op_sel:[0,1] op_sel_hi:[1,1]
	v_pk_mul_f32 v[10:11], v[10:11], v[114:115] op_sel:[0,1] op_sel_hi:[1,1]
	v_pk_mul_f32 v[12:13], v[12:13], v[114:115] op_sel:[0,1] op_sel_hi:[1,1]
	v_pk_mul_f32 v[14:15], v[14:15], v[114:115] op_sel:[0,1] op_sel_hi:[1,1]
	v_pk_mul_f32 v[8:9], v[8:9], v[0:1]
	v_pk_mul_f32 v[10:11], v[10:11], v[2:3]
	v_pk_mul_f32 v[12:13], v[12:13], v[4:5]
	v_pk_mul_f32 v[14:15], v[14:15], v[6:7]
	v_cvt_pk_bf16_f32 v60, v8, v9
	v_cvt_pk_bf16_f32 v61, v10, v11
	v_cvt_pk_bf16_f32 v62, v12, v13
	v_cvt_pk_bf16_f32 v63, v14, v15
	global_store_dwordx4 v[22:23], v[60:63], off offset:2560
	s_waitcnt vmcnt(15)
	v_lshlrev_b32_e32 v8, 16, v64
	v_and_b32_e32 v9, s10, v64
	v_lshlrev_b32_e32 v10, 16, v65
	v_and_b32_e32 v11, s10, v65
	v_lshlrev_b32_e32 v12, 16, v66
	v_and_b32_e32 v13, s10, v66
	v_lshlrev_b32_e32 v14, 16, v67
	v_and_b32_e32 v15, s10, v67
	v_pk_mul_f32 v[8:9], v[8:9], v[116:117] op_sel_hi:[1,0]
	v_pk_mul_f32 v[10:11], v[10:11], v[116:117] op_sel_hi:[1,0]
	v_pk_mul_f32 v[12:13], v[12:13], v[116:117] op_sel_hi:[1,0]
	v_pk_mul_f32 v[14:15], v[14:15], v[116:117] op_sel_hi:[1,0]
	v_pk_mul_f32 v[8:9], v[8:9], v[0:1]
	v_pk_mul_f32 v[10:11], v[10:11], v[2:3]
	v_pk_mul_f32 v[12:13], v[12:13], v[4:5]
	v_pk_mul_f32 v[14:15], v[14:15], v[6:7]
	v_cvt_pk_bf16_f32 v64, v8, v9
	v_cvt_pk_bf16_f32 v65, v10, v11
	v_cvt_pk_bf16_f32 v66, v12, v13
	v_cvt_pk_bf16_f32 v67, v14, v15
	global_store_dwordx4 v[24:25], v[64:67], off offset:2560
	s_waitcnt vmcnt(15)
	v_lshlrev_b32_e32 v8, 16, v68
	v_and_b32_e32 v9, s10, v68
	v_lshlrev_b32_e32 v10, 16, v69
	v_and_b32_e32 v11, s10, v69
	v_lshlrev_b32_e32 v12, 16, v70
	v_and_b32_e32 v13, s10, v70
	v_lshlrev_b32_e32 v14, 16, v71
	v_and_b32_e32 v15, s10, v71
	v_pk_mul_f32 v[8:9], v[8:9], v[116:117] op_sel:[0,1] op_sel_hi:[1,1]
	v_pk_mul_f32 v[10:11], v[10:11], v[116:117] op_sel:[0,1] op_sel_hi:[1,1]
	v_pk_mul_f32 v[12:13], v[12:13], v[116:117] op_sel:[0,1] op_sel_hi:[1,1]
	v_pk_mul_f32 v[14:15], v[14:15], v[116:117] op_sel:[0,1] op_sel_hi:[1,1]
	v_pk_mul_f32 v[8:9], v[8:9], v[0:1]
	v_pk_mul_f32 v[10:11], v[10:11], v[2:3]
	v_pk_mul_f32 v[12:13], v[12:13], v[4:5]
	v_pk_mul_f32 v[14:15], v[14:15], v[6:7]
	v_cvt_pk_bf16_f32 v68, v8, v9
	v_cvt_pk_bf16_f32 v69, v10, v11
	v_cvt_pk_bf16_f32 v70, v12, v13
	v_cvt_pk_bf16_f32 v71, v14, v15
	global_store_dwordx4 v[26:27], v[68:71], off offset:2560
	s_waitcnt vmcnt(15)
	v_lshlrev_b32_e32 v8, 16, v72
	v_and_b32_e32 v9, s10, v72
	v_lshlrev_b32_e32 v10, 16, v73
	v_and_b32_e32 v11, s10, v73
	v_lshlrev_b32_e32 v12, 16, v74
	v_and_b32_e32 v13, s10, v74
	v_lshlrev_b32_e32 v14, 16, v75
	v_and_b32_e32 v15, s10, v75
	v_pk_mul_f32 v[8:9], v[8:9], v[118:119] op_sel_hi:[1,0]
	v_pk_mul_f32 v[10:11], v[10:11], v[118:119] op_sel_hi:[1,0]
	v_pk_mul_f32 v[12:13], v[12:13], v[118:119] op_sel_hi:[1,0]
	v_pk_mul_f32 v[14:15], v[14:15], v[118:119] op_sel_hi:[1,0]
	v_pk_mul_f32 v[8:9], v[8:9], v[0:1]
	v_pk_mul_f32 v[10:11], v[10:11], v[2:3]
	v_pk_mul_f32 v[12:13], v[12:13], v[4:5]
	v_pk_mul_f32 v[14:15], v[14:15], v[6:7]
	v_cvt_pk_bf16_f32 v72, v8, v9
	v_cvt_pk_bf16_f32 v73, v10, v11
	v_cvt_pk_bf16_f32 v74, v12, v13
	v_cvt_pk_bf16_f32 v75, v14, v15
	global_store_dwordx4 v[28:29], v[72:75], off offset:2560
	s_waitcnt vmcnt(15)
	v_lshlrev_b32_e32 v8, 16, v76
	v_and_b32_e32 v9, s10, v76
	v_lshlrev_b32_e32 v10, 16, v77
	v_and_b32_e32 v11, s10, v77
	v_lshlrev_b32_e32 v12, 16, v78
	v_and_b32_e32 v13, s10, v78
	v_lshlrev_b32_e32 v14, 16, v79
	v_and_b32_e32 v15, s10, v79
	v_pk_mul_f32 v[8:9], v[8:9], v[118:119] op_sel:[0,1] op_sel_hi:[1,1]
	v_pk_mul_f32 v[10:11], v[10:11], v[118:119] op_sel:[0,1] op_sel_hi:[1,1]
	v_pk_mul_f32 v[12:13], v[12:13], v[118:119] op_sel:[0,1] op_sel_hi:[1,1]
	v_pk_mul_f32 v[14:15], v[14:15], v[118:119] op_sel:[0,1] op_sel_hi:[1,1]
	v_pk_mul_f32 v[8:9], v[8:9], v[0:1]
	v_pk_mul_f32 v[10:11], v[10:11], v[2:3]
	v_pk_mul_f32 v[12:13], v[12:13], v[4:5]
	v_pk_mul_f32 v[14:15], v[14:15], v[6:7]
	v_cvt_pk_bf16_f32 v76, v8, v9
	v_cvt_pk_bf16_f32 v77, v10, v11
	v_cvt_pk_bf16_f32 v78, v12, v13
	v_cvt_pk_bf16_f32 v79, v14, v15
	global_store_dwordx4 v[30:31], v[76:79], off offset:2560
	s_waitcnt vmcnt(15)
	v_lshlrev_b32_e32 v8, 16, v80
	v_and_b32_e32 v9, s10, v80
	v_lshlrev_b32_e32 v10, 16, v81
	v_and_b32_e32 v11, s10, v81
	v_lshlrev_b32_e32 v12, 16, v82
	v_and_b32_e32 v13, s10, v82
	v_lshlrev_b32_e32 v14, 16, v83
	v_and_b32_e32 v15, s10, v83
	v_pk_mul_f32 v[8:9], v[8:9], v[120:121] op_sel_hi:[1,0]
	v_pk_mul_f32 v[10:11], v[10:11], v[120:121] op_sel_hi:[1,0]
	v_pk_mul_f32 v[12:13], v[12:13], v[120:121] op_sel_hi:[1,0]
	v_pk_mul_f32 v[14:15], v[14:15], v[120:121] op_sel_hi:[1,0]
	v_pk_mul_f32 v[8:9], v[8:9], v[0:1]
	v_pk_mul_f32 v[10:11], v[10:11], v[2:3]
	v_pk_mul_f32 v[12:13], v[12:13], v[4:5]
	v_pk_mul_f32 v[14:15], v[14:15], v[6:7]
	v_cvt_pk_bf16_f32 v80, v8, v9
	v_cvt_pk_bf16_f32 v81, v10, v11
	v_cvt_pk_bf16_f32 v82, v12, v13
	v_cvt_pk_bf16_f32 v83, v14, v15
	global_store_dwordx4 v[32:33], v[80:83], off offset:2560
	s_waitcnt vmcnt(15)
; __device__ __forceinline__ unsigned cvt_pk_bf16(float lo, float hi) { unsigned r; asm volatile("v_cvt_pk_bf16_f32 %0, %1, %2" : "=v"(r) : "v"(lo), "v"(hi)); return r; }
; __device__ __forceinline__ float bflo(unsigned w) { return __uint_as_float(w << 16); }
; __device__ __forceinline__ float bfhi(unsigned w) { return __uint_as_float(w & 0xffff0000u); }
; __device__ void phase_ssd_out(KP P, int layer, LAS unsigned char* lds) {
;     ...
;             for (int lt = 0; lt < 8; ++lt) { const int l = lt * 16 + r; float t = 0.f;
; #pragma unroll
;                 for (int w = 0; w < 8; ++w) t += red[w * 128 + l];
;                 const float rstd = rsqrtf(t * (1.f / 512.f) + EPS);
;                 bf16_t* zp = zbase + (long)l * PW + q * 4; u32x2 v[4];
; #pragma unroll
;                 for (int pt = 0; pt < 4; ++pt) v[pt] = *(const u32x2*)(zp + pt * 16);
; #pragma unroll
;                 for (int pt = 0; pt < 4; ++pt) { u32x2 o; o.x = cvt_pk_bf16(bflo(v[pt].x) * rstd * nwv[pt][0], bfhi(v[pt].x) * rstd * nwv[pt][1]);
;                     o.y = cvt_pk_bf16(bflo(v[pt].y) * rstd * nwv[pt][2], bfhi(v[pt].y) * rstd * nwv[pt][3]); *(u32x2*)(zp + pt * 16) = o; }
;                 }
	v_lshlrev_b32_e32 v8, 16, v84
	v_and_b32_e32 v9, s10, v84
	v_lshlrev_b32_e32 v10, 16, v85
	v_and_b32_e32 v11, s10, v85
	v_lshlrev_b32_e32 v12, 16, v86
	v_and_b32_e32 v13, s10, v86
	v_lshlrev_b32_e32 v14, 16, v87
	v_and_b32_e32 v15, s10, v87
	v_pk_mul_f32 v[8:9], v[8:9], v[120:121] op_sel:[0,1] op_sel_hi:[1,1]
	v_pk_mul_f32 v[10:11], v[10:11], v[120:121] op_sel:[0,1] op_sel_hi:[1,1]
	v_pk_mul_f32 v[12:13], v[12:13], v[120:121] op_sel:[0,1] op_sel_hi:[1,1]
	v_pk_mul_f32 v[14:15], v[14:15], v[120:121] op_sel:[0,1] op_sel_hi:[1,1]
	v_pk_mul_f32 v[8:9], v[8:9], v[0:1]
	v_pk_mul_f32 v[10:11], v[10:11], v[2:3]
	v_pk_mul_f32 v[12:13], v[12:13], v[4:5]
	v_pk_mul_f32 v[14:15], v[14:15], v[6:7]
	v_cvt_pk_bf16_f32 v84, v8, v9
	v_cvt_pk_bf16_f32 v85, v10, v11
	v_cvt_pk_bf16_f32 v86, v12, v13
	v_cvt_pk_bf16_f32 v87, v14, v15
	global_store_dwordx4 v[34:35], v[84:87], off offset:2560
	s_waitcnt vmcnt(15)
	v_lshlrev_b32_e32 v8, 16, v88
	v_and_b32_e32 v9, s10, v88
	v_lshlrev_b32_e32 v10, 16, v89
	v_and_b32_e32 v11, s10, v89
	v_lshlrev_b32_e32 v12, 16, v90
	v_and_b32_e32 v13, s10, v90
	v_lshlrev_b32_e32 v14, 16, v91
	v_and_b32_e32 v15, s10, v91
	v_pk_mul_f32 v[8:9], v[8:9], v[122:123] op_sel_hi:[1,0]
	v_pk_mul_f32 v[10:11], v[10:11], v[122:123] op_sel_hi:[1,0]
	v_pk_mul_f32 v[12:13], v[12:13], v[122:123] op_sel_hi:[1,0]
	v_pk_mul_f32 v[14:15], v[14:15], v[122:123] op_sel_hi:[1,0]
	v_pk_mul_f32 v[8:9], v[8:9], v[0:1]
	v_pk_mul_f32 v[10:11], v[10:11], v[2:3]
	v_pk_mul_f32 v[12:13], v[12:13], v[4:5]
	v_pk_mul_f32 v[14:15], v[14:15], v[6:7]
	v_cvt_pk_bf16_f32 v88, v8, v9
	v_cvt_pk_bf16_f32 v89, v10, v11
	v_cvt_pk_bf16_f32 v90, v12, v13
	v_cvt_pk_bf16_f32 v91, v14, v15
	global_store_dwordx4 v[36:37], v[88:91], off offset:2560
	s_waitcnt vmcnt(15)
	v_lshlrev_b32_e32 v8, 16, v92
	v_and_b32_e32 v9, s10, v92
	v_lshlrev_b32_e32 v10, 16, v93
	v_and_b32_e32 v11, s10, v93
	v_lshlrev_b32_e32 v12, 16, v94
	v_and_b32_e32 v13, s10, v94
	v_lshlrev_b32_e32 v14, 16, v95
	v_and_b32_e32 v15, s10, v95
	v_pk_mul_f32 v[8:9], v[8:9], v[122:123] op_sel:[0,1] op_sel_hi:[1,1]
	v_pk_mul_f32 v[10:11], v[10:11], v[122:123] op_sel:[0,1] op_sel_hi:[1,1]
	v_pk_mul_f32 v[12:13], v[12:13], v[122:123] op_sel:[0,1] op_sel_hi:[1,1]
	v_pk_mul_f32 v[14:15], v[14:15], v[122:123] op_sel:[0,1] op_sel_hi:[1,1]
	v_pk_mul_f32 v[8:9], v[8:9], v[0:1]
	v_pk_mul_f32 v[10:11], v[10:11], v[2:3]
	v_pk_mul_f32 v[12:13], v[12:13], v[4:5]
	v_pk_mul_f32 v[14:15], v[14:15], v[6:7]
	v_cvt_pk_bf16_f32 v92, v8, v9
	v_cvt_pk_bf16_f32 v93, v10, v11
	v_cvt_pk_bf16_f32 v94, v12, v13
	v_cvt_pk_bf16_f32 v95, v14, v15
	global_store_dwordx4 v[38:39], v[92:95], off offset:2560
	s_waitcnt vmcnt(15)
	v_lshlrev_b32_e32 v8, 16, v96
	v_and_b32_e32 v9, s10, v96
	v_lshlrev_b32_e32 v10, 16, v97
	v_and_b32_e32 v11, s10, v97
	v_lshlrev_b32_e32 v12, 16, v98
	v_and_b32_e32 v13, s10, v98
	v_lshlrev_b32_e32 v14, 16, v99
	v_and_b32_e32 v15, s10, v99
	v_pk_mul_f32 v[8:9], v[8:9], v[124:125] op_sel_hi:[1,0]
	v_pk_mul_f32 v[10:11], v[10:11], v[124:125] op_sel_hi:[1,0]
	v_pk_mul_f32 v[12:13], v[12:13], v[124:125] op_sel_hi:[1,0]
	v_pk_mul_f32 v[14:15], v[14:15], v[124:125] op_sel_hi:[1,0]
	v_pk_mul_f32 v[8:9], v[8:9], v[0:1]
	v_pk_mul_f32 v[10:11], v[10:11], v[2:3]
	v_pk_mul_f32 v[12:13], v[12:13], v[4:5]
	v_pk_mul_f32 v[14:15], v[14:15], v[6:7]
	v_cvt_pk_bf16_f32 v96, v8, v9
	v_cvt_pk_bf16_f32 v97, v10, v11
	v_cvt_pk_bf16_f32 v98, v12, v13
	v_cvt_pk_bf16_f32 v99, v14, v15
	global_store_dwordx4 v[40:41], v[96:99], off offset:2560
	s_waitcnt vmcnt(15)
	v_lshlrev_b32_e32 v8, 16, v100
	v_and_b32_e32 v9, s10, v100
	v_lshlrev_b32_e32 v10, 16, v101
	v_and_b32_e32 v11, s10, v101
	v_lshlrev_b32_e32 v12, 16, v102
	v_and_b32_e32 v13, s10, v102
	v_lshlrev_b32_e32 v14, 16, v103
	v_and_b32_e32 v15, s10, v103
	v_pk_mul_f32 v[8:9], v[8:9], v[124:125] op_sel:[0,1] op_sel_hi:[1,1]
	v_pk_mul_f32 v[10:11], v[10:11], v[124:125] op_sel:[0,1] op_sel_hi:[1,1]
	v_pk_mul_f32 v[12:13], v[12:13], v[124:125] op_sel:[0,1] op_sel_hi:[1,1]
	v_pk_mul_f32 v[14:15], v[14:15], v[124:125] op_sel:[0,1] op_sel_hi:[1,1]
	v_pk_mul_f32 v[8:9], v[8:9], v[0:1]
	v_pk_mul_f32 v[10:11], v[10:11], v[2:3]
	v_pk_mul_f32 v[12:13], v[12:13], v[4:5]
	v_pk_mul_f32 v[14:15], v[14:15], v[6:7]
	v_cvt_pk_bf16_f32 v100, v8, v9
	v_cvt_pk_bf16_f32 v101, v10, v11
	v_cvt_pk_bf16_f32 v102, v12, v13
	v_cvt_pk_bf16_f32 v103, v14, v15
	global_store_dwordx4 v[42:43], v[100:103], off offset:2560
	s_waitcnt vmcnt(15)
	v_lshlrev_b32_e32 v8, 16, v104
	v_and_b32_e32 v9, s10, v104
	v_lshlrev_b32_e32 v10, 16, v105
	v_and_b32_e32 v11, s10, v105
	v_lshlrev_b32_e32 v12, 16, v106
	v_and_b32_e32 v13, s10, v106
	v_lshlrev_b32_e32 v14, 16, v107
	v_and_b32_e32 v15, s10, v107
	v_pk_mul_f32 v[8:9], v[8:9], v[126:127] op_sel_hi:[1,0]
	v_pk_mul_f32 v[10:11], v[10:11], v[126:127] op_sel_hi:[1,0]
	v_pk_mul_f32 v[12:13], v[12:13], v[126:127] op_sel_hi:[1,0]
	v_pk_mul_f32 v[14:15], v[14:15], v[126:127] op_sel_hi:[1,0]
	v_pk_mul_f32 v[8:9], v[8:9], v[0:1]
	v_pk_mul_f32 v[10:11], v[10:11], v[2:3]
	v_pk_mul_f32 v[12:13], v[12:13], v[4:5]
	v_pk_mul_f32 v[14:15], v[14:15], v[6:7]
	v_cvt_pk_bf16_f32 v104, v8, v9
	v_cvt_pk_bf16_f32 v105, v10, v11
	v_cvt_pk_bf16_f32 v106, v12, v13
	v_cvt_pk_bf16_f32 v107, v14, v15
	global_store_dwordx4 v[44:45], v[104:107], off offset:2560
	s_waitcnt vmcnt(15)
	v_lshlrev_b32_e32 v8, 16, v108
	v_and_b32_e32 v9, s10, v108
	v_lshlrev_b32_e32 v10, 16, v109
	v_and_b32_e32 v11, s10, v109
	v_lshlrev_b32_e32 v12, 16, v110
	v_and_b32_e32 v13, s10, v110
	v_lshlrev_b32_e32 v14, 16, v111
	v_and_b32_e32 v15, s10, v111
	v_pk_mul_f32 v[8:9], v[8:9], v[126:127] op_sel:[0,1] op_sel_hi:[1,1]
	v_pk_mul_f32 v[10:11], v[10:11], v[126:127] op_sel:[0,1] op_sel_hi:[1,1]
	v_pk_mul_f32 v[12:13], v[12:13], v[126:127] op_sel:[0,1] op_sel_hi:[1,1]
	v_pk_mul_f32 v[14:15], v[14:15], v[126:127] op_sel:[0,1] op_sel_hi:[1,1]
	v_pk_mul_f32 v[8:9], v[8:9], v[0:1]
	v_pk_mul_f32 v[10:11], v[10:11], v[2:3]
	v_pk_mul_f32 v[12:13], v[12:13], v[4:5]
	v_pk_mul_f32 v[14:15], v[14:15], v[6:7]
	v_cvt_pk_bf16_f32 v108, v8, v9
	v_cvt_pk_bf16_f32 v109, v10, v11
	v_cvt_pk_bf16_f32 v110, v12, v13
	v_cvt_pk_bf16_f32 v111, v14, v15
	global_store_dwordx4 v[46:47], v[108:111], off offset:2560
	s_add_i32 s22, s22, s1
	s_cmpk_gt_i32 s22, 0x1ff
	s_cbranch_scc1 .LBB0_48
